# v27: grid-barrier poll loop without s_sleep (faster release detection)
# baseline (speedup 1.0000x reference)
.LBB0_537:
	s_nop 0
	global_load_dword v0, v1, s[0:1] sc1
	s_waitcnt vmcnt(0)
	v_cmp_gt_u32_e32 vcc, s3, v0
	s_cbranch_vccnz .LBB0_537

.LBB0_549:
	s_nop 0
	global_load_dword v2, v1, s[4:5] offset:32 sc1
	s_waitcnt vmcnt(0)
	v_and_b32_e32 v2, 0xffff0000, v2
	v_cmp_ne_u32_e32 vcc, v2, v0
	s_or_b64 s[6:7], vcc, s[6:7]
	s_andn2_b64 exec, exec, s[6:7]
	s_cbranch_execnz .LBB0_549
	s_branch .LBB0_2
